# GDN (iii): block-product operand reads issued with the norm reads (fresh VGPRs, counted waits); HGRN2: redundant barrier A at the chunk top removed (both layers); on top of GDN (vi) read hoist
# speedup vs baseline: 1.0070x; 1.0043x over previous
; #define LDS_BARRIER() do { asm volatile("s_waitcnt lgkmcnt(0)" ::: "memory"); __builtin_amdgcn_s_barrier(); asm volatile("" ::: "memory"); } while (0)
; __device__ __forceinline__ unsigned pk2(float lo, float hi) { const f32x2_t v = {lo, hi}; return __builtin_bit_cast(unsigned, __builtin_convertvector(v, bf16x2_t)); }
; __device__ __forceinline__ void phase_hg2(Frame& F, int j, bool ctx_out, bool dry = false) {
;     ...
;                 LDS_BARRIER();
;                 unsigned kp[8]; float pr0[8], pr1[8]; float tot0 = 1.f, tot1 = 1.f;
;                 {
;                     float f0[8], f1[8];
; #pragma unroll
;                     for (int i = 0; i < 8; ++i) {
;                         const float xf0 = bflo(rf[i]), xf1 = bfhi(rf[i]);
;                         const float ex0 = __expf(-fabsf(xf0)), rc0 = __builtin_amdgcn_rcpf(1.f + ex0), ex1 = __expf(-fabsf(xf1)), rc1 = __builtin_amdgcn_rcpf(1.f + ex1);
;                         const float sp0 = (xf0 >= 0.f) ? rc0 : ex0 * rc0, sn0 = (xf0 >= 0.f) ? ex0 * rc0 : rc0, sp1 = (xf1 >= 0.f) ? rc1 : ex1 * rc1, sn1 = (xf1 >= 0.f) ? ex1 * rc1 : rc1;
;                         kp[i] = pk2((1.f - lb0) * sn0, (1.f - lb1) * sn1);
;                         f0[i] = fmaxf(lb0 + (1.f - lb0) * sp0, 1e-30f); f1[i] = fmaxf(lb1 + (1.f - lb1) * sp1, 1e-30f);
;                     }
;                     if (seg >= 4) {
; #pragma unroll
;                         for (int i = 0; i < 8; ++i) { tot0 = fmaxf(tot0 * f0[i], 1e-30f); tot1 = fmaxf(tot1 * f1[i], 1e-30f); pr0[i] = tot0; pr1[i] = tot1; }
;                     } else {
; #pragma unroll
;                         for (int i = 7; i >= 0; --i) { pr0[i] = tot0; pr1[i] = tot1; tot0 = fmaxf(tot0 * f0[i], 1e-30f); tot1 = fmaxf(tot1 * f1[i], 1e-30f); }
;                     }
.LBB0_256:
	s_waitcnt vmcnt(0)
	v_lshlrev_b32_e32 v2, 16, v171
	v_and_b32_e32 v3, 0xffff0000, v171
	v_mul_f32_e64 v0, |v2|, s78
	v_exp_f32_e32 v0, v0
	v_mul_f32_e64 v1, |v3|, s78
	v_exp_f32_e32 v1, v1
	v_and_b32_e32 v5, 0xffff0000, v169
	v_add_f32_e32 v4, 1.0, v0
	v_rcp_f32_e32 v40, v4
	v_add_f32_e32 v4, 1.0, v1
	v_rcp_f32_e32 v41, v4
	v_lshlrev_b32_e32 v4, 16, v169
	v_cmp_le_f32_e64 s[44:45], 0, v4
	v_cmp_le_f32_e64 s[46:47], 0, v5
	v_pk_mul_f32 v[42:43], v[0:1], v[40:41]
	v_mul_f32_e64 v0, |v4|, s78
	v_exp_f32_e32 v0, v0
	v_mul_f32_e64 v1, |v5|, s78
	v_exp_f32_e32 v1, v1
	v_lshlrev_b32_e32 v4, 16, v174
	v_add_f32_e32 v6, 1.0, v0
	v_rcp_f32_e32 v46, v6
	v_add_f32_e32 v6, 1.0, v1
	v_rcp_f32_e32 v47, v6
	v_and_b32_e32 v5, 0xffff0000, v174
	v_and_b32_e32 v7, 0xffff0000, v172
	v_and_b32_e32 v9, 0xffff0000, v170
	v_pk_mul_f32 v[48:49], v[0:1], v[46:47]
	v_mul_f32_e64 v0, |v4|, s78
	v_exp_f32_e32 v0, v0
	v_mul_f32_e64 v1, |v5|, s78
	v_exp_f32_e32 v1, v1
	v_and_b32_e32 v11, 0xffff0000, v175
	v_add_f32_e32 v6, 1.0, v0
	v_rcp_f32_e32 v50, v6
	v_add_f32_e32 v6, 1.0, v1
	v_rcp_f32_e32 v51, v6
	v_lshlrev_b32_e32 v6, 16, v172
	v_and_b32_e32 v13, 0xffff0000, v173
	v_and_b32_e32 v15, 0xffff0000, v176
	v_pk_mul_f32 v[84:85], v[0:1], v[50:51]
	v_mul_f32_e64 v0, |v6|, s78
	v_exp_f32_e32 v0, v0
	v_mul_f32_e64 v1, |v7|, s78
	v_exp_f32_e32 v1, v1
	v_cmp_le_f32_e64 s[40:41], 0, v2
	v_add_f32_e32 v8, 1.0, v0
	v_rcp_f32_e32 v86, v8
	v_add_f32_e32 v8, 1.0, v1
	v_rcp_f32_e32 v87, v8
	v_lshlrev_b32_e32 v8, 16, v170
	v_cndmask_b32_e64 v2, v42, v40, s[40:41]
	v_cmp_le_f32_e64 s[42:43], 0, v3
	v_pk_mul_f32 v[88:89], v[0:1], v[86:87]
	v_mul_f32_e64 v0, |v8|, s78
	v_exp_f32_e32 v0, v0
	v_mul_f32_e64 v1, |v9|, s78
	v_exp_f32_e32 v1, v1
	v_cndmask_b32_e64 v3, v43, v41, s[42:43]
	v_add_f32_e32 v10, 1.0, v0
	v_rcp_f32_e32 v90, v10
	v_add_f32_e32 v10, 1.0, v1
	v_rcp_f32_e32 v91, v10
	v_lshlrev_b32_e32 v10, 16, v175
	v_add_f32_e32 v2, 0, v2
	v_cmp_le_f32_e64 s[38:39], 0, v15
	v_pk_mul_f32 v[92:93], v[0:1], v[90:91]
	v_mul_f32_e64 v0, |v10|, s78
	v_exp_f32_e32 v0, v0
	v_mul_f32_e64 v1, |v11|, s78
	v_exp_f32_e32 v1, v1
	v_mov_b32_e32 v16, v122
	v_add_f32_e32 v12, 1.0, v0
	v_rcp_f32_e32 v94, v12
	v_add_f32_e32 v12, 1.0, v1
	v_rcp_f32_e32 v95, v12
	v_lshlrev_b32_e32 v12, 16, v173
	v_mov_b32_e32 v100, v124
	v_mov_b32_e32 v177, v123
	v_pk_mul_f32 v[96:97], v[0:1], v[94:95]
	v_mul_f32_e64 v0, |v12|, s78
	v_exp_f32_e32 v0, v0
	v_mul_f32_e64 v1, |v13|, s78
	v_exp_f32_e32 v1, v1
	v_max_f32_e32 v44, 0xda24260, v2
	v_add_f32_e32 v14, 1.0, v0
	v_rcp_f32_e32 v98, v14
	v_add_f32_e32 v14, 1.0, v1
	v_rcp_f32_e32 v99, v14
	v_lshlrev_b32_e32 v14, 16, v176
	v_cmp_le_f32_e64 s[36:37], 0, v14
	v_add_f32_e32 v2, 0, v3
	v_pk_mul_f32 v[108:109], v[0:1], v[98:99]
	v_mul_f32_e64 v0, |v14|, s78
	v_exp_f32_e32 v0, v0
	v_mul_f32_e64 v1, |v15|, s78
	v_exp_f32_e32 v1, v1
	v_cmp_le_f32_e64 s[48:49], 0, v4
	v_add_f32_e32 v17, 1.0, v0
	v_rcp_f32_e32 v28, v17
	v_add_f32_e32 v17, 1.0, v1
	v_rcp_f32_e32 v29, v17
	v_cmp_le_f32_e64 s[50:51], 0, v5
	v_cmp_le_f32_e64 s[52:53], 0, v6
	v_cmp_le_f32_e64 s[54:55], 0, v7
	v_pk_mul_f32 v[30:31], v[0:1], v[28:29]
	v_cmp_le_f32_e64 s[56:57], 0, v8
	v_cndmask_b32_e64 v0, v30, v28, s[36:37]
	v_cmp_le_f32_e64 s[58:59], 0, v9
	v_cmp_le_f32_e64 s[62:63], 0, v10
	v_cmp_le_f32_e64 s[64:65], 0, v11
	v_cmp_le_f32_e64 s[66:67], 0, v12
	v_cmp_le_f32_e64 s[68:69], 0, v13
	v_cndmask_b32_e64 v1, v31, v29, s[38:39]
	v_add_f32_e32 v0, 0, v0
	s_waitcnt lgkmcnt(0)
	s_nop 0
	v_max_f32_e32 v45, 0xda24260, v2
	v_cndmask_b32_e64 v2, v48, v46, s[44:45]
	v_cndmask_b32_e64 v3, v49, v47, s[46:47]
	v_cndmask_b32_e64 v4, v84, v50, s[48:49]
	v_cndmask_b32_e64 v5, v85, v51, s[50:51]
	v_cndmask_b32_e64 v6, v88, v86, s[52:53]
	v_cndmask_b32_e64 v7, v89, v87, s[54:55]
	v_cndmask_b32_e64 v8, v92, v90, s[56:57]
	v_cndmask_b32_e64 v9, v93, v91, s[58:59]
	v_cndmask_b32_e64 v10, v96, v94, s[62:63]
	v_cndmask_b32_e64 v11, v97, v95, s[64:65]
	v_cndmask_b32_e64 v12, v108, v98, s[66:67]
	v_cndmask_b32_e64 v13, v109, v99, s[68:69]
	v_max_f32_e32 v32, 0xda24260, v0
	v_add_f32_e32 v0, 0, v1
	v_add_f32_e32 v2, 0, v2
	v_add_f32_e32 v3, 0, v3
	v_add_f32_e32 v4, 0, v4
	v_add_f32_e32 v5, 0, v5
	v_add_f32_e32 v6, 0, v6
	v_add_f32_e32 v7, 0, v7
	v_add_f32_e32 v8, 0, v8
	v_add_f32_e32 v9, 0, v9
	v_add_f32_e32 v10, 0, v10
	v_add_f32_e32 v11, 0, v11
	v_add_f32_e32 v12, 0, v12
	v_add_f32_e32 v13, 0, v13
	v_max_f32_e32 v33, 0xda24260, v0
	v_cndmask_b32_e64 v0, 0, 1, s[70:71]
	v_max_f32_e32 v2, 0xda24260, v2
	v_max_f32_e32 v3, 0xda24260, v3
	v_max_f32_e32 v4, 0xda24260, v4
	v_max_f32_e32 v5, 0xda24260, v5
	v_max_f32_e32 v6, 0xda24260, v6
	v_max_f32_e32 v7, 0xda24260, v7
	v_max_f32_e32 v8, 0xda24260, v8
	v_max_f32_e32 v9, 0xda24260, v9
	v_max_f32_e32 v10, 0xda24260, v10
	v_max_f32_e32 v11, 0xda24260, v11
	v_max_f32_e32 v12, 0xda24260, v12
	v_max_f32_e32 v13, 0xda24260, v13
	v_cmp_ne_u32_e64 s[60:61], 1, v0
	s_andn2_b64 vcc, exec, s[70:71]
	s_mov_b64 s[8:9], -1
	s_cbranch_vccnz .LBB0_258
	v_mul_f32_e32 v0, v12, v32
	v_max_f32_e32 v34, 0xda24260, v0
	v_mul_f32_e32 v0, v13, v33
	v_max_f32_e32 v35, 0xda24260, v0
	v_mul_f32_e32 v0, v10, v34
	v_max_f32_e32 v36, 0xda24260, v0
	v_mul_f32_e32 v0, v11, v35
	v_max_f32_e32 v37, 0xda24260, v0
	v_mul_f32_e32 v0, v8, v36
	v_max_f32_e32 v110, 0xda24260, v0
	v_mul_f32_e32 v0, v9, v37
	v_max_f32_e32 v111, 0xda24260, v0
	v_mul_f32_e32 v0, v6, v110
	v_max_f32_e32 v112, 0xda24260, v0
	v_mul_f32_e32 v0, v7, v111
	v_max_f32_e32 v113, 0xda24260, v0
	v_mul_f32_e32 v0, v4, v112
	v_max_f32_e32 v114, 0xda24260, v0
	v_mul_f32_e32 v0, v5, v113
	v_max_f32_e32 v115, 0xda24260, v0
	v_mul_f32_e32 v0, v2, v114
	v_max_f32_e32 v15, 0xda24260, v0
	v_mul_f32_e32 v0, v3, v115
	v_max_f32_e32 v14, 0xda24260, v0
	v_mul_f32_e32 v0, v44, v15
	v_mul_f32_e32 v1, v45, v14
	v_max_f32_e32 v0, 0xda24260, v0
	v_max_f32_e32 v1, 0xda24260, v1
	s_mov_b64 s[8:9], 0

; #define LAS __attribute__((address_space(3)))
; template <int CTRL> __device__ __forceinline__ float dppf(float x) { return __builtin_bit_cast(float, __builtin_amdgcn_mov_dpp(__builtin_bit_cast(int, x), CTRL, 0xf, 0xf, true)); }
; #define MFMA16(a, b, c) __builtin_amdgcn_mfma_f32_16x16x32_bf16((a), (b), (c), 0, 0, 0)
; __device__ __forceinline__ void phase_gdn2(Frame& F, bool ctx_out, bool dry = false) {
;     ...
;                 {
;                     const int t = tid >> 3, which = (tid >> 2) & 1, part = tid & 3;
;                     const LAS v4u* src = (const LAS v4u*)((which ? KC : QC) + t * GS + part * 32);
;                     float ss = 0.f;
; #pragma unroll
;                     for (int u = 0; u < 4; ++u) { const v4u x = src[u]; const float f0 = bflo(x.x), f1 = bfhi(x.x), f2 = bflo(x.y), f3 = bfhi(x.y), f4 = bflo(x.z), f5 = bfhi(x.z), f6 = bflo(x.w), f7 = bfhi(x.w);
;                         ss += (f0 * f0 + f1 * f1) + (f2 * f2 + f3 * f3) + (f4 * f4 + f5 * f5) + (f6 * f6 + f7 * f7); }
;                     ss += dppf<0xB1>(ss); ss += dppf<0x4E>(ss);
;                     if (part == 0) { const float r = __builtin_amdgcn_rsqf(ss + RMS_EPS); if (which) s_rk[t] = r; else s_rq[t] = r * 0.08838834764831845f; }
;                 }
;                 f32x4 blk = (f32x4){0.f, 0.f, 0.f, 0.f};
;                 const int bI = vb & 3;
;                 {
;                     LAS bf16* bimg = (vb < 4) ? KC : QC;
; #pragma unroll
;                     for (int ks = 0; ks < 4; ++ks) { const hb8 fa = *(const LAS hb8*)(KC + (bI * 16 + l15) * GS + ks * 32 + q4 * 8), fb = *(const LAS hb8*)(bimg + (bI * 16 + l15) * GS + ks * 32 + q4 * 8);
;                         blk = MFMA16(fa, fb, blk); }
;                 }
.LBB0_974:
	v_and_b32_e32 v1, 4, v100
	v_and_b32_e32 v101, 3, v100
	v_mov_b32_e32 v84, s62
	v_cmp_eq_u32_e32 vcc, 0, v1
	v_lshlrev_b32_e32 v85, 6, v101
	s_waitcnt lgkmcnt(0)
	s_barrier
	v_cndmask_b32_e32 v1, 0, v84, vcc
	v_mul_lo_u32 v84, v0, s44
	v_add3_u32 v1, v1, v84, v85
	ds_read_b128 v[84:87], v1
	ds_read_b128 v[88:91], v1 offset:16
	ds_read_b128 v[92:95], v1 offset:32
	ds_read_b128 v[96:99], v1 offset:48
	v_and_b32_e32 v137, 15, v3
	v_or_b32_e32 v186, s66, v137
	v_mul_u32_u24_e32 v187, 0x88, v186
	v_lshlrev_b32_e32 v187, 1, v187
	v_and_b32_e32 v141, -16, v3
	v_add3_u32 v188, 0, v187, v141
	v_add3_u32 v189, s64, v187, v141
	ds_read_b128 v[154:157], v188
	ds_read_b128 v[158:161], v189
	ds_read_b128 v[162:165], v188 offset:64
	ds_read_b128 v[166:169], v189 offset:64
	ds_read_b128 v[170:173], v188 offset:128
	ds_read_b128 v[174:177], v189 offset:128
	ds_read_b128 v[178:181], v188 offset:192
	ds_read_b128 v[182:185], v189 offset:192
	v_cmp_eq_u32_e64 s[14:15], 0, v101
	s_waitcnt lgkmcnt(11)
	v_lshlrev_b32_e32 v1, 16, v84
	v_and_b32_e32 v84, 0xffff0000, v84
	v_lshlrev_b32_e32 v102, 16, v85
	v_and_b32_e32 v85, 0xffff0000, v85
	v_mul_f32_e32 v84, v84, v84
	v_fmac_f32_e32 v84, v1, v1
	v_mul_f32_e32 v1, v85, v85
	v_lshlrev_b32_e32 v103, 16, v86
	v_and_b32_e32 v86, 0xffff0000, v86
	v_fmac_f32_e32 v1, v102, v102
	v_add_f32_e32 v1, v84, v1
	v_mul_f32_e32 v84, v86, v86
	v_lshlrev_b32_e32 v104, 16, v87
	v_and_b32_e32 v87, 0xffff0000, v87
	v_fmac_f32_e32 v84, v103, v103
	v_add_f32_e32 v1, v84, v1
	v_mul_f32_e32 v84, v87, v87
	v_fmac_f32_e32 v84, v104, v104
	s_waitcnt lgkmcnt(10)
	v_and_b32_e32 v85, 0xffff0000, v88
	v_add_f32_e32 v1, v84, v1
	v_lshlrev_b32_e32 v84, 16, v88
	v_and_b32_e32 v87, 0xffff0000, v89
	v_mul_f32_e32 v85, v85, v85
	v_lshlrev_b32_e32 v86, 16, v89
	v_fmac_f32_e32 v85, v84, v84
	v_mul_f32_e32 v84, v87, v87
	v_and_b32_e32 v89, 0xffff0000, v90
	v_fmac_f32_e32 v84, v86, v86
	v_lshlrev_b32_e32 v88, 16, v90
	v_add_f32_e32 v84, v85, v84
	v_mul_f32_e32 v85, v89, v89
	v_lshlrev_b32_e32 v90, 16, v91
	v_and_b32_e32 v91, 0xffff0000, v91
	v_fmac_f32_e32 v85, v88, v88
	v_add_f32_e32 v84, v85, v84
	v_mul_f32_e32 v85, v91, v91
	v_fmac_f32_e32 v85, v90, v90
	v_add_f32_e32 v84, v85, v84
	s_waitcnt lgkmcnt(9)
	v_and_b32_e32 v85, 0xffff0000, v92
	v_add_f32_e32 v1, v1, v84
	v_lshlrev_b32_e32 v84, 16, v92
	v_and_b32_e32 v87, 0xffff0000, v93
	v_mul_f32_e32 v85, v85, v85
	v_lshlrev_b32_e32 v86, 16, v93
	v_fmac_f32_e32 v85, v84, v84
	v_mul_f32_e32 v84, v87, v87
	v_and_b32_e32 v89, 0xffff0000, v94
	v_fmac_f32_e32 v84, v86, v86
	v_lshlrev_b32_e32 v88, 16, v94
	v_add_f32_e32 v84, v85, v84
	v_mul_f32_e32 v85, v89, v89
	v_and_b32_e32 v91, 0xffff0000, v95
	v_fmac_f32_e32 v85, v88, v88
	v_lshlrev_b32_e32 v90, 16, v95
	v_add_f32_e32 v84, v85, v84
	v_mul_f32_e32 v85, v91, v91
	v_fmac_f32_e32 v85, v90, v90
	v_add_f32_e32 v84, v85, v84
	s_waitcnt lgkmcnt(8)
	v_and_b32_e32 v85, 0xffff0000, v96
	v_add_f32_e32 v1, v1, v84
	v_lshlrev_b32_e32 v84, 16, v96
	v_and_b32_e32 v87, 0xffff0000, v97
	v_mul_f32_e32 v85, v85, v85
	v_lshlrev_b32_e32 v86, 16, v97
	v_fmac_f32_e32 v85, v84, v84
	v_mul_f32_e32 v84, v87, v87
	v_and_b32_e32 v89, 0xffff0000, v98
	v_fmac_f32_e32 v84, v86, v86
	v_lshlrev_b32_e32 v88, 16, v98
	v_add_f32_e32 v84, v85, v84
	v_mul_f32_e32 v85, v89, v89
	v_and_b32_e32 v91, 0xffff0000, v99
	v_fmac_f32_e32 v85, v88, v88
	v_lshlrev_b32_e32 v90, 16, v99
	v_add_f32_e32 v84, v85, v84
	v_mul_f32_e32 v85, v91, v91
	v_fmac_f32_e32 v85, v90, v90
	v_add_f32_e32 v84, v85, v84
	v_add_f32_e32 v1, v1, v84
	s_nop 1
	v_add_f32_dpp v1, v1, v1 quad_perm:[1,0,3,2] row_mask:0xf bank_mask:0xf bound_ctrl:1
	s_nop 1
	v_mov_b32_dpp v84, v1 quad_perm:[2,3,0,1] row_mask:0xf bank_mask:0xf bound_ctrl:1
	s_and_saveexec_b64 s[30:31], s[14:15]
	s_cbranch_execz .LBB0_976
	v_add_f32_e32 v1, v1, v84
	v_add_f32_e32 v1, 0x358637bd, v1
	v_rsq_f32_e32 v1, v1
	v_mov_b32_e32 v84, s40
	v_mov_b32_e32 v85, s45
	v_cndmask_b32_e32 v84, v84, v85, vcc
	v_mul_f32_e32 v85, 0x3db504f3, v1
	v_cndmask_b32_e32 v1, v1, v85, vcc
	v_lshl_add_u32 v0, v0, 2, v84
	ds_write_b32 v0, v1
.LBB0_976:
	s_or_b64 exec, exec, s[30:31]
	v_or_b32_e32 v0, s66, v137
	s_bitcmp1_b32 s52, 0
	v_ashrrev_i32_e32 v138, 4, v3
	s_cselect_b32 s14, 0x340, 0
	s_add_i32 s76, s14, 0
	s_add_i32 s76, s76, 0x24400
	s_mov_b64 s[30:31], -1
	s_waitcnt lgkmcnt(6)
	v_mfma_f32_16x16x32_bf16 v[84:87], v[154:157], v[158:161], 0
	s_waitcnt lgkmcnt(4)
	v_mfma_f32_16x16x32_bf16 v[84:87], v[162:165], v[166:169], v[84:87]
	s_waitcnt lgkmcnt(2)
	v_mfma_f32_16x16x32_bf16 v[84:87], v[170:173], v[174:177], v[84:87]
	v_lshlrev_b32_e32 v1, 2, v138
	s_waitcnt lgkmcnt(0)
	v_mfma_f32_16x16x32_bf16 v[84:87], v[178:181], v[182:185], v[84:87]
	v_add_lshl_u32 v88, v1, s66, 2
	s_barrier
	v_lshl_add_u32 v95, v0, 2, s76
	v_add_u32_e32 v89, s76, v88
	v_add_u32_e32 v88, 0, v88
	ds_read_b32 v97, v95 offset:256
	ds_read_b128 v[102:105], v89 offset:256
	v_add_u32_e32 v88, 0x24c80, v88
	ds_read_b128 v[88:91], v88
	s_and_b64 vcc, exec, s[42:43]
	v_cmp_lt_i32_e64 s[14:15], v1, v137
	v_mul_u32_u24_e32 v92, 0x50, v0
	v_lshlrev_b32_e32 v139, 1, v1
	s_waitcnt lgkmcnt(1)
	v_sub_f32_e32 v99, v97, v102
	v_sub_f32_e32 v96, v97, v103
	v_or_b32_e32 v94, 3, v1
	v_or_b32_e32 v93, 2, v1
	v_sub_f32_e32 v98, v97, v104
	v_sub_f32_e32 v97, v97, v105
	s_cbranch_vccz .LBB0_992
	v_mul_f32_e32 v101, 0x3fb8aa3b, v99
	v_exp_f32_e32 v101, v101
	s_waitcnt lgkmcnt(0)
	v_mul_f32_e32 v102, v84, v88
	v_mul_f32_e32 v103, 0x3fb8aa3b, v97
	v_exp_f32_e32 v103, v103
	v_mul_f32_e32 v101, v102, v101
	v_mul_f32_e32 v102, 0x3fb8aa3b, v96
	v_exp_f32_e32 v105, v102
	v_mul_f32_e32 v102, 0x3fb8aa3b, v98
	v_exp_f32_e32 v102, v102
	v_mul_f32_e32 v104, v85, v89
	v_mul_f32_e32 v104, v104, v105
	v_cmp_le_i32_e32 vcc, v1, v137
	v_cndmask_b32_e64 v106, 0, v104, s[14:15]
	v_pk_mul_f32 v[104:105], v[86:87], v[90:91]
	v_cndmask_b32_e32 v101, 0, v101, vcc
	v_pk_mul_f32 v[102:103], v[104:105], v[102:103]
	v_cvt_pk_bf16_f32 v104, v101, v106
	v_cvt_pk_bf16_f32 v101, v102, v103
	v_cmp_le_i32_e32 vcc, v93, v137
	s_mov_b32 s14, 0x5040100
	s_nop 0
	v_cndmask_b32_e32 v102, 0, v101, vcc
	v_cmp_le_i32_e32 vcc, v94, v137
	s_nop 1
	v_cndmask_b32_sdwa v101, v2, v101, vcc dst_sel:DWORD dst_unused:UNUSED_PAD src0_sel:DWORD src1_sel:WORD_1
	v_perm_b32 v105, v101, v102, s14
	v_add3_u32 v101, s85, v92, v139
	ds_write_b64 v101, v[104:105]
	v_lshlrev_b32_e32 v140, 2, v1
	s_cbranch_execz .LBB0_993

; #define LDS_BARRIER() do { asm volatile("s_waitcnt lgkmcnt(0)" ::: "memory"); __builtin_amdgcn_s_barrier(); asm volatile("" ::: "memory"); } while (0)
; __device__ __forceinline__ unsigned pk2(float lo, float hi) { const f32x2_t v = {lo, hi}; return __builtin_bit_cast(unsigned, __builtin_convertvector(v, bf16x2_t)); }
; __device__ __forceinline__ void phase_hg2(Frame& F, int j, bool ctx_out, bool dry = false) {
;     ...
;                 LDS_BARRIER();
;                 unsigned kp[8]; float pr0[8], pr1[8]; float tot0 = 1.f, tot1 = 1.f;
;                 {
;                     float f0[8], f1[8];
; #pragma unroll
;                     for (int i = 0; i < 8; ++i) {
;                         const float xf0 = bflo(rf[i]), xf1 = bfhi(rf[i]);
;                         const float ex0 = __expf(-fabsf(xf0)), rc0 = __builtin_amdgcn_rcpf(1.f + ex0), ex1 = __expf(-fabsf(xf1)), rc1 = __builtin_amdgcn_rcpf(1.f + ex1);
;                         const float sp0 = (xf0 >= 0.f) ? rc0 : ex0 * rc0, sn0 = (xf0 >= 0.f) ? ex0 * rc0 : rc0, sp1 = (xf1 >= 0.f) ? rc1 : ex1 * rc1, sn1 = (xf1 >= 0.f) ? ex1 * rc1 : rc1;
;                         kp[i] = pk2((1.f - lb0) * sn0, (1.f - lb1) * sn1);
;                         f0[i] = fmaxf(lb0 + (1.f - lb0) * sp0, 1e-30f); f1[i] = fmaxf(lb1 + (1.f - lb1) * sp1, 1e-30f);
;                     }
;                     if (seg >= 4) {
; #pragma unroll
;                         for (int i = 0; i < 8; ++i) { tot0 = fmaxf(tot0 * f0[i], 1e-30f); tot1 = fmaxf(tot1 * f1[i], 1e-30f); pr0[i] = tot0; pr1[i] = tot1; }
;                     } else {
; #pragma unroll
;                         for (int i = 7; i >= 0; --i) { pr0[i] = tot0; pr1[i] = tot1; tot0 = fmaxf(tot0 * f0[i], 1e-30f); tot1 = fmaxf(tot1 * f1[i], 1e-30f); }
;                     }
.LBB0_2346:
	v_lshlrev_b32_e32 v2, 16, v176
	v_and_b32_e32 v3, 0xffff0000, v176
	v_mul_f32_e64 v0, |v2|, s10
	v_exp_f32_e32 v0, v0
	v_mul_f32_e64 v1, |v3|, s10
	v_exp_f32_e32 v1, v1
	v_and_b32_e32 v5, 0xffff0000, v175
	v_add_f32_e32 v4, 1.0, v0
	v_rcp_f32_e32 v42, v4
	v_add_f32_e32 v4, 1.0, v1
	v_rcp_f32_e32 v43, v4
	v_lshlrev_b32_e32 v4, 16, v175
	v_cmp_le_f32_e64 s[46:47], 0, v4
	v_cmp_le_f32_e64 s[48:49], 0, v5
	v_pk_mul_f32 v[44:45], v[0:1], v[42:43]
	v_mul_f32_e64 v0, |v4|, s10
	v_exp_f32_e32 v0, v0
	v_mul_f32_e64 v1, |v5|, s10
	v_exp_f32_e32 v1, v1
	s_waitcnt vmcnt(15)
	v_lshlrev_b32_e32 v4, 16, v180
	v_add_f32_e32 v6, 1.0, v0
	v_rcp_f32_e32 v46, v6
	v_add_f32_e32 v6, 1.0, v1
	v_rcp_f32_e32 v47, v6
	v_and_b32_e32 v5, 0xffff0000, v180
	s_waitcnt vmcnt(12)
	v_and_b32_e32 v7, 0xffff0000, v178
	s_waitcnt vmcnt(9)
	v_and_b32_e32 v9, 0xffff0000, v177
	v_pk_mul_f32 v[48:49], v[0:1], v[46:47]
	v_mul_f32_e64 v0, |v4|, s10
	v_exp_f32_e32 v0, v0
	v_mul_f32_e64 v1, |v5|, s10
	v_exp_f32_e32 v1, v1
	s_waitcnt vmcnt(6)
	v_and_b32_e32 v11, 0xffff0000, v181
	v_add_f32_e32 v6, 1.0, v0
	v_rcp_f32_e32 v50, v6
	v_add_f32_e32 v6, 1.0, v1
	v_rcp_f32_e32 v51, v6
	v_lshlrev_b32_e32 v6, 16, v178
	s_waitcnt vmcnt(3)
	v_and_b32_e32 v13, 0xffff0000, v179
	s_waitcnt vmcnt(0)
	v_and_b32_e32 v15, 0xffff0000, v182
	v_pk_mul_f32 v[84:85], v[0:1], v[50:51]
	v_mul_f32_e64 v0, |v6|, s10
	v_exp_f32_e32 v0, v0
	v_mul_f32_e64 v1, |v7|, s10
	v_exp_f32_e32 v1, v1
	v_cmp_le_f32_e64 s[42:43], 0, v2
	v_add_f32_e32 v8, 1.0, v0
	v_rcp_f32_e32 v86, v8
	v_add_f32_e32 v8, 1.0, v1
	v_rcp_f32_e32 v87, v8
	v_lshlrev_b32_e32 v8, 16, v177
	v_cndmask_b32_e64 v2, v44, v42, s[42:43]
	v_cmp_le_f32_e64 s[44:45], 0, v3
	v_pk_mul_f32 v[88:89], v[0:1], v[86:87]
	v_mul_f32_e64 v0, |v8|, s10
	v_exp_f32_e32 v0, v0
	v_mul_f32_e64 v1, |v9|, s10
	v_exp_f32_e32 v1, v1
	v_cndmask_b32_e64 v3, v45, v43, s[44:45]
	v_add_f32_e32 v10, 1.0, v0
	v_rcp_f32_e32 v90, v10
	v_add_f32_e32 v10, 1.0, v1
	v_rcp_f32_e32 v91, v10
	v_lshlrev_b32_e32 v10, 16, v181
	v_fma_f32 v2, v112, v2, v110
	v_cmp_le_f32_e64 s[40:41], 0, v15
	v_pk_mul_f32 v[92:93], v[0:1], v[90:91]
	v_mul_f32_e64 v0, |v10|, s10
	v_exp_f32_e32 v0, v0
	v_mul_f32_e64 v1, |v11|, s10
	v_exp_f32_e32 v1, v1
	v_mov_b32_e32 v16, v101
	v_add_f32_e32 v12, 1.0, v0
	v_rcp_f32_e32 v94, v12
	v_add_f32_e32 v12, 1.0, v1
	v_rcp_f32_e32 v95, v12
	v_lshlrev_b32_e32 v12, 16, v179
	v_mov_b32_e32 v102, v129
	v_mov_b32_e32 v183, v128
	v_pk_mul_f32 v[96:97], v[0:1], v[94:95]
	v_mul_f32_e64 v0, |v12|, s10
	v_exp_f32_e32 v0, v0
	v_mul_f32_e64 v1, |v13|, s10
	v_exp_f32_e32 v1, v1
	v_max_f32_e32 v40, 0xda24260, v2
	v_add_f32_e32 v14, 1.0, v0
	v_rcp_f32_e32 v98, v14
	v_add_f32_e32 v14, 1.0, v1
	v_rcp_f32_e32 v99, v14
	v_lshlrev_b32_e32 v14, 16, v182
	v_cmp_le_f32_e64 s[38:39], 0, v14
	v_fma_f32 v2, v113, v3, v111
	v_pk_mul_f32 v[114:115], v[0:1], v[98:99]
	v_mul_f32_e64 v0, |v14|, s10
	v_exp_f32_e32 v0, v0
	v_mul_f32_e64 v1, |v15|, s10
	v_exp_f32_e32 v1, v1
	v_cmp_le_f32_e64 s[50:51], 0, v4
	v_add_f32_e32 v17, 1.0, v0
	v_rcp_f32_e32 v28, v17
	v_add_f32_e32 v17, 1.0, v1
	v_rcp_f32_e32 v29, v17
	v_cmp_le_f32_e64 s[52:53], 0, v5
	v_cmp_le_f32_e64 s[54:55], 0, v6
	v_cmp_le_f32_e64 s[56:57], 0, v7
	v_pk_mul_f32 v[30:31], v[0:1], v[28:29]
	v_cmp_le_f32_e64 s[58:59], 0, v8
	v_cndmask_b32_e64 v0, v30, v28, s[38:39]
	v_cmp_le_f32_e64 s[60:61], 0, v9
	v_cmp_le_f32_e64 s[64:65], 0, v10
	v_cmp_le_f32_e64 s[66:67], 0, v11
	v_cmp_le_f32_e64 s[68:69], 0, v12
	v_cmp_le_f32_e64 s[70:71], 0, v13
	v_cndmask_b32_e64 v1, v31, v29, s[40:41]
	v_fma_f32 v0, v112, v0, v110
	s_waitcnt lgkmcnt(0)
	s_nop 0
	v_max_f32_e32 v41, 0xda24260, v2
	v_cndmask_b32_e64 v2, v48, v46, s[46:47]
	v_cndmask_b32_e64 v3, v49, v47, s[48:49]
	v_cndmask_b32_e64 v4, v84, v50, s[50:51]
	v_cndmask_b32_e64 v5, v85, v51, s[52:53]
	v_cndmask_b32_e64 v6, v88, v86, s[54:55]
	v_cndmask_b32_e64 v7, v89, v87, s[56:57]
	v_cndmask_b32_e64 v8, v92, v90, s[58:59]
	v_cndmask_b32_e64 v9, v93, v91, s[60:61]
	v_cndmask_b32_e64 v10, v96, v94, s[64:65]
	v_cndmask_b32_e64 v11, v97, v95, s[66:67]
	v_cndmask_b32_e64 v12, v114, v98, s[68:69]
	v_cndmask_b32_e64 v13, v115, v99, s[70:71]
	v_max_f32_e32 v32, 0xda24260, v0
	v_fma_f32 v0, v113, v1, v111
	v_fma_f32 v2, v112, v2, v110
	v_fma_f32 v3, v113, v3, v111
	v_fma_f32 v4, v112, v4, v110
	v_fma_f32 v5, v113, v5, v111
	v_fma_f32 v6, v112, v6, v110
	v_fma_f32 v7, v113, v7, v111
	v_fma_f32 v8, v112, v8, v110
	v_fma_f32 v9, v113, v9, v111
	v_fma_f32 v10, v112, v10, v110
	v_fma_f32 v11, v113, v11, v111
	v_fma_f32 v12, v112, v12, v110
	v_fma_f32 v13, v113, v13, v111
	v_max_f32_e32 v33, 0xda24260, v0
	v_cndmask_b32_e64 v0, 0, 1, s[76:77]
	v_max_f32_e32 v2, 0xda24260, v2
	v_max_f32_e32 v3, 0xda24260, v3
	v_max_f32_e32 v4, 0xda24260, v4
	v_max_f32_e32 v5, 0xda24260, v5
	v_max_f32_e32 v6, 0xda24260, v6
	v_max_f32_e32 v7, 0xda24260, v7
	v_max_f32_e32 v8, 0xda24260, v8
	v_max_f32_e32 v9, 0xda24260, v9
	v_max_f32_e32 v10, 0xda24260, v10
	v_max_f32_e32 v11, 0xda24260, v11
	v_max_f32_e32 v12, 0xda24260, v12
	v_max_f32_e32 v13, 0xda24260, v13
	v_cmp_ne_u32_e64 s[62:63], 1, v0
	s_andn2_b64 vcc, exec, s[76:77]
	s_mov_b64 s[36:37], -1
	s_cbranch_vccnz .LBB0_2348
	v_mul_f32_e32 v0, v12, v32
	v_max_f32_e32 v34, 0xda24260, v0
	v_mul_f32_e32 v0, v13, v33
	v_max_f32_e32 v35, 0xda24260, v0
	v_mul_f32_e32 v0, v10, v34
	v_max_f32_e32 v36, 0xda24260, v0
	v_mul_f32_e32 v0, v11, v35
	v_max_f32_e32 v37, 0xda24260, v0
	v_mul_f32_e32 v0, v8, v36
	v_max_f32_e32 v116, 0xda24260, v0
	v_mul_f32_e32 v0, v9, v37
	v_max_f32_e32 v117, 0xda24260, v0
	v_mul_f32_e32 v0, v6, v116
	v_max_f32_e32 v118, 0xda24260, v0
	v_mul_f32_e32 v0, v7, v117
	v_max_f32_e32 v119, 0xda24260, v0
	v_mul_f32_e32 v0, v4, v118
	v_max_f32_e32 v120, 0xda24260, v0
	v_mul_f32_e32 v0, v5, v119
	v_max_f32_e32 v121, 0xda24260, v0
	v_mul_f32_e32 v0, v2, v120
	v_max_f32_e32 v15, 0xda24260, v0
	v_mul_f32_e32 v0, v3, v121
	v_max_f32_e32 v14, 0xda24260, v0
	v_mul_f32_e32 v0, v40, v15
	v_mul_f32_e32 v1, v41, v14
	v_max_f32_e32 v0, 0xda24260, v0
	v_max_f32_e32 v1, 0xda24260, v1
	s_mov_b64 s[36:37], 0
